# adds: proj gate-unit epilogue: all four bias-gate vectors loaded up front (no mid-epilogue wait behind the stores)
# speedup vs baseline: 1.0518x; 1.0063x over previous
; __device__ __forceinline__ unsigned cvt_pk_bf16(float lo, float hi) { const f32x2 v = {lo, hi}; const bf16x2_t b = __builtin_convertvector(v, bf16x2_t); return __builtin_bit_cast(unsigned, b); }
; __device__ __forceinline__ float fast_sigmoid(float x) { return __builtin_amdgcn_rcpf(1.0f + __builtin_amdgcn_exp2f(-x * LOG2E)); }
;     __device__ __forceinline__ void operator()(const f32x4 (&acc)[2][2][4][2], const Unit& u, int wr, int wc, int fr, int fq) const {
;     ...
;         if ((u.j & 1) == 0) {
; #pragma unroll
;             for (int bj = 0; bj < 2; ++bj) { const f32x4 b0 = *(const f32x4*)(bgate + br * 1024 + col00 + bj * 128), b1 = *(const f32x4*)(bgate + br * 1024 + col00 + bj * 128 + 4);
; #pragma unroll
;                 for (int ai = 0; ai < 2; ++ai)
; #pragma unroll
;                     for (int m = 0; m < 4; ++m) { f32x4 v0 = acc[ai][bj][m][0] + b0, v1 = acc[ai][bj][m][1] + b1;
; #pragma unroll
;                         for (int i = 0; i < 4; ++i) { v0[i] = fast_sigmoid(v0[i]); v1[i] = fast_sigmoid(v1[i]); }
;                         u32x4 w; w.x = cvt_pk_bf16(v0[0], v0[1]); w.y = cvt_pk_bf16(v0[2], v0[3]); w.z = cvt_pk_bf16(v1[0], v1[1]); w.w = cvt_pk_bf16(v1[2], v1[3]);
;                         *((u32x4*)Gs + ((size_t)(tile * 16 + (ai * 2 + bj) * 4 + m) * NTHREADS + tid)) = w; } }
.LBB0_402:
	s_lshl_b32 s12, s19, 10
	s_ashr_i32 s13, s12, 31
	s_lshl_b32 s44, s18, 4
	s_lshl_b64 s[12:13], s[12:13], 2
	s_add_u32 s12, s65, s12
	v_ashrrev_i32_e32 v135, 31, v134
	s_addc_u32 s13, s68, s13
	v_lshl_add_u64 v[152:153], v[134:135], 2, s[12:13]
	global_load_dwordx4 v[202:205], v[152:153], off
	global_load_dwordx4 v[206:209], v[152:153], off offset:16
	global_load_dwordx4 v[210:213], v[152:153], off offset:512
	global_load_dwordx4 v[214:217], v[152:153], off offset:528
	s_ashr_i32 s45, s44, 31
	s_lshl_b64 s[12:13], s[44:45], 13
	s_waitcnt vmcnt(0)
	v_pk_add_f32 v[124:125], v[124:125], v[208:209]
	v_pk_add_f32 v[122:123], v[122:123], v[206:207]
	v_mul_f32_e32 v124, 0xbfb8aa3b, v124
	v_mul_f32_e32 v122, 0xbfb8aa3b, v122
	v_mul_f32_e32 v123, 0xbfb8aa3b, v123
	v_exp_f32_e32 v122, v122
	v_exp_f32_e32 v123, v123
	v_exp_f32_e32 v124, v124
	v_pk_add_f32 v[128:129], v[128:129], v[204:205]
	v_pk_add_f32 v[126:127], v[126:127], v[202:203]
	v_add_f32_e32 v122, 1.0, v122
	v_add_f32_e32 v123, 1.0, v123
	v_add_f32_e32 v124, 1.0, v124
	v_mul_f32_e32 v126, 0xbfb8aa3b, v126
	v_rcp_f32_e32 v154, v122
	v_mul_f32_e32 v122, 0xbfb8aa3b, v127
	v_rcp_f32_e32 v127, v123
	v_mul_f32_e32 v123, 0xbfb8aa3b, v128
	v_rcp_f32_e32 v128, v124
	v_mul_f32_e32 v124, 0xbfb8aa3b, v129
	v_mul_f32_e32 v125, 0xbfb8aa3b, v125
	v_exp_f32_e32 v126, v126
	v_exp_f32_e32 v122, v122
	v_exp_f32_e32 v123, v123
	v_exp_f32_e32 v124, v124
	v_exp_f32_e32 v125, v125
	v_pk_add_f32 v[116:117], v[116:117], v[208:209]
	v_pk_add_f32 v[114:115], v[114:115], v[206:207]
	v_add_f32_e32 v126, 1.0, v126
	v_add_f32_e32 v122, 1.0, v122
	v_add_f32_e32 v123, 1.0, v123
	v_add_f32_e32 v124, 1.0, v124
	v_add_f32_e32 v125, 1.0, v125
	v_mul_f32_e32 v114, 0xbfb8aa3b, v114
	v_mul_f32_e32 v115, 0xbfb8aa3b, v115
	v_mul_f32_e32 v116, 0xbfb8aa3b, v116
	v_rcp_f32_e32 v126, v126
	v_rcp_f32_e32 v122, v122
	v_rcp_f32_e32 v123, v123
	v_rcp_f32_e32 v124, v124
	v_rcp_f32_e32 v125, v125
	v_exp_f32_e32 v114, v114
	v_exp_f32_e32 v115, v115
	v_exp_f32_e32 v116, v116
	v_cvt_pk_bf16_f32 v122, v126, v122
	v_cvt_pk_bf16_f32 v123, v123, v124
	v_cvt_pk_bf16_f32 v124, v154, v127
	v_cvt_pk_bf16_f32 v125, v128, v125
	v_lshl_add_u64 v[126:127], v[146:147], 0, s[12:13]
	v_pk_add_f32 v[120:121], v[120:121], v[204:205]
	v_pk_add_f32 v[118:119], v[118:119], v[202:203]
	v_add_f32_e32 v114, 1.0, v114
	v_add_f32_e32 v115, 1.0, v115
	v_add_f32_e32 v116, 1.0, v116
	v_mov_b32_e32 v230, v122
	v_mov_b32_e32 v231, v123
	v_mov_b32_e32 v232, v124
	v_mov_b32_e32 v233, v125
	v_mul_f32_e32 v118, 0xbfb8aa3b, v118
	v_mul_f32_e32 v117, 0xbfb8aa3b, v117
	v_rcp_f32_e32 v122, v114
	v_mul_f32_e32 v114, 0xbfb8aa3b, v119
	v_rcp_f32_e32 v119, v115
	v_mul_f32_e32 v115, 0xbfb8aa3b, v120
	v_rcp_f32_e32 v120, v116
	v_mul_f32_e32 v116, 0xbfb8aa3b, v121
	v_exp_f32_e32 v118, v118
	v_exp_f32_e32 v114, v114
	v_exp_f32_e32 v115, v115
	v_exp_f32_e32 v116, v116
	v_exp_f32_e32 v117, v117
	v_pk_add_f32 v[108:109], v[108:109], v[208:209]
	v_pk_add_f32 v[106:107], v[106:107], v[206:207]
	v_add_f32_e32 v118, 1.0, v118
	v_add_f32_e32 v114, 1.0, v114
	v_add_f32_e32 v115, 1.0, v115
	v_add_f32_e32 v116, 1.0, v116
	v_add_f32_e32 v117, 1.0, v117
	v_mul_f32_e32 v106, 0xbfb8aa3b, v106
	v_mul_f32_e32 v107, 0xbfb8aa3b, v107
	v_mul_f32_e32 v108, 0xbfb8aa3b, v108
	v_rcp_f32_e32 v118, v118
	v_rcp_f32_e32 v114, v114
	v_rcp_f32_e32 v115, v115
	v_rcp_f32_e32 v116, v116
	v_rcp_f32_e32 v117, v117
	v_exp_f32_e32 v106, v106
	v_exp_f32_e32 v107, v107
	v_exp_f32_e32 v108, v108
	s_or_b32 s12, s44, 1
	s_ashr_i32 s13, s12, 31
	s_lshl_b64 s[12:13], s[12:13], 13
	v_cvt_pk_bf16_f32 v114, v118, v114
	v_cvt_pk_bf16_f32 v115, v115, v116
	v_cvt_pk_bf16_f32 v116, v122, v119
	v_cvt_pk_bf16_f32 v117, v120, v117
	v_lshl_add_u64 v[118:119], v[146:147], 0, s[12:13]
	v_pk_add_f32 v[112:113], v[112:113], v[204:205]
	v_pk_add_f32 v[110:111], v[110:111], v[202:203]
	v_add_f32_e32 v106, 1.0, v106
	v_add_f32_e32 v107, 1.0, v107
	v_add_f32_e32 v108, 1.0, v108
	v_mov_b32_e32 v234, v114
	v_mov_b32_e32 v235, v115
	v_mov_b32_e32 v236, v116
	v_mov_b32_e32 v237, v117
	v_mul_f32_e32 v110, 0xbfb8aa3b, v110
	v_mul_f32_e32 v109, 0xbfb8aa3b, v109
	v_rcp_f32_e32 v114, v106
	v_mul_f32_e32 v106, 0xbfb8aa3b, v111
	v_rcp_f32_e32 v111, v107
	v_mul_f32_e32 v107, 0xbfb8aa3b, v112
	v_rcp_f32_e32 v112, v108
	v_mul_f32_e32 v108, 0xbfb8aa3b, v113
	v_exp_f32_e32 v110, v110
	v_exp_f32_e32 v106, v106
	v_exp_f32_e32 v107, v107
	v_exp_f32_e32 v108, v108
	v_exp_f32_e32 v109, v109
	v_pk_add_f32 v[100:101], v[100:101], v[208:209]
	v_pk_add_f32 v[98:99], v[98:99], v[206:207]
	v_add_f32_e32 v110, 1.0, v110
	v_add_f32_e32 v106, 1.0, v106
	v_add_f32_e32 v107, 1.0, v107
	v_add_f32_e32 v108, 1.0, v108
	v_add_f32_e32 v109, 1.0, v109
	v_mul_f32_e32 v98, 0xbfb8aa3b, v98
	v_mul_f32_e32 v99, 0xbfb8aa3b, v99
	v_mul_f32_e32 v100, 0xbfb8aa3b, v100
	v_rcp_f32_e32 v110, v110
	v_rcp_f32_e32 v106, v106
	v_rcp_f32_e32 v107, v107
	v_rcp_f32_e32 v108, v108
	v_rcp_f32_e32 v109, v109
	v_exp_f32_e32 v98, v98
	v_exp_f32_e32 v99, v99
	v_exp_f32_e32 v100, v100
	s_or_b32 s12, s44, 2
	s_ashr_i32 s13, s12, 31
	s_lshl_b64 s[12:13], s[12:13], 13
	v_cvt_pk_bf16_f32 v106, v110, v106
	v_cvt_pk_bf16_f32 v107, v107, v108
	v_cvt_pk_bf16_f32 v108, v114, v111
	v_cvt_pk_bf16_f32 v109, v112, v109
	v_lshl_add_u64 v[110:111], v[146:147], 0, s[12:13]
	v_pk_add_f32 v[104:105], v[104:105], v[204:205]
	v_pk_add_f32 v[102:103], v[102:103], v[202:203]
	v_add_f32_e32 v98, 1.0, v98
	v_add_f32_e32 v99, 1.0, v99
	v_add_f32_e32 v100, 1.0, v100
	v_mov_b32_e32 v238, v106
	v_mov_b32_e32 v239, v107
	v_mov_b32_e32 v240, v108
	v_mov_b32_e32 v241, v109
	v_mul_f32_e32 v102, 0xbfb8aa3b, v102
; __device__ __forceinline__ unsigned cvt_pk_bf16(float lo, float hi) { const f32x2 v = {lo, hi}; const bf16x2_t b = __builtin_convertvector(v, bf16x2_t); return __builtin_bit_cast(unsigned, b); }
; __device__ __forceinline__ float fast_sigmoid(float x) { return __builtin_amdgcn_rcpf(1.0f + __builtin_amdgcn_exp2f(-x * LOG2E)); }
;     __device__ __forceinline__ void operator()(const f32x4 (&acc)[2][2][4][2], const Unit& u, int wr, int wc, int fr, int fq) const {
;     ...
;             for (int bj = 0; bj < 2; ++bj) { const f32x4 b0 = *(const f32x4*)(bgate + br * 1024 + col00 + bj * 128), b1 = *(const f32x4*)(bgate + br * 1024 + col00 + bj * 128 + 4);
; #pragma unroll
;                 for (int ai = 0; ai < 2; ++ai)
; #pragma unroll
;                     for (int m = 0; m < 4; ++m) { f32x4 v0 = acc[ai][bj][m][0] + b0, v1 = acc[ai][bj][m][1] + b1;
; #pragma unroll
;                         for (int i = 0; i < 4; ++i) { v0[i] = fast_sigmoid(v0[i]); v1[i] = fast_sigmoid(v1[i]); }
;                         u32x4 w; w.x = cvt_pk_bf16(v0[0], v0[1]); w.y = cvt_pk_bf16(v0[2], v0[3]); w.z = cvt_pk_bf16(v1[0], v1[1]); w.w = cvt_pk_bf16(v1[2], v1[3]);
;                         *((u32x4*)Gs + ((size_t)(tile * 16 + (ai * 2 + bj) * 4 + m) * NTHREADS + tid)) = w; } }
	v_mul_f32_e32 v101, 0xbfb8aa3b, v101
	v_rcp_f32_e32 v106, v98
	v_mul_f32_e32 v98, 0xbfb8aa3b, v103
	v_rcp_f32_e32 v103, v99
	v_mul_f32_e32 v99, 0xbfb8aa3b, v104
	v_rcp_f32_e32 v104, v100
	v_mul_f32_e32 v100, 0xbfb8aa3b, v105
	v_exp_f32_e32 v102, v102
	v_exp_f32_e32 v98, v98
	v_exp_f32_e32 v99, v99
	v_exp_f32_e32 v100, v100
	v_exp_f32_e32 v101, v101
	v_pk_add_f32 v[92:93], v[92:93], v[208:209]
	v_pk_add_f32 v[90:91], v[90:91], v[206:207]
	v_add_f32_e32 v102, 1.0, v102
	v_add_f32_e32 v98, 1.0, v98
	v_add_f32_e32 v99, 1.0, v99
	v_add_f32_e32 v100, 1.0, v100
	v_add_f32_e32 v101, 1.0, v101
	v_mul_f32_e32 v90, 0xbfb8aa3b, v90
	v_mul_f32_e32 v91, 0xbfb8aa3b, v91
	v_mul_f32_e32 v92, 0xbfb8aa3b, v92
	v_rcp_f32_e32 v102, v102
	v_rcp_f32_e32 v98, v98
	v_rcp_f32_e32 v99, v99
	v_rcp_f32_e32 v100, v100
	v_rcp_f32_e32 v101, v101
	v_exp_f32_e32 v90, v90
	v_exp_f32_e32 v91, v91
	v_exp_f32_e32 v92, v92
	s_or_b32 s12, s44, 3
	s_ashr_i32 s13, s12, 31
	s_lshl_b64 s[12:13], s[12:13], 13
	v_cvt_pk_bf16_f32 v98, v102, v98
	v_cvt_pk_bf16_f32 v99, v99, v100
	v_cvt_pk_bf16_f32 v100, v106, v103
	v_cvt_pk_bf16_f32 v101, v104, v101
	v_lshl_add_u64 v[102:103], v[146:147], 0, s[12:13]
	v_pk_add_f32 v[96:97], v[96:97], v[204:205]
	v_pk_add_f32 v[94:95], v[94:95], v[202:203]
	v_add_f32_e32 v90, 1.0, v90
	v_add_f32_e32 v91, 1.0, v91
	v_add_f32_e32 v92, 1.0, v92
	v_mov_b32_e32 v242, v98
	v_mov_b32_e32 v243, v99
	v_mov_b32_e32 v244, v100
	v_mov_b32_e32 v245, v101
	v_mul_f32_e32 v94, 0xbfb8aa3b, v94
	v_mul_f32_e32 v93, 0xbfb8aa3b, v93
	v_rcp_f32_e32 v98, v90
	v_mul_f32_e32 v90, 0xbfb8aa3b, v95
	v_rcp_f32_e32 v95, v91
	v_mul_f32_e32 v91, 0xbfb8aa3b, v96
	v_rcp_f32_e32 v96, v92
	v_mul_f32_e32 v92, 0xbfb8aa3b, v97
	v_exp_f32_e32 v94, v94
	v_exp_f32_e32 v90, v90
	v_exp_f32_e32 v91, v91
	v_exp_f32_e32 v92, v92
	v_exp_f32_e32 v93, v93
	v_pk_add_f32 v[84:85], v[84:85], v[208:209]
	v_pk_add_f32 v[82:83], v[82:83], v[206:207]
	v_add_f32_e32 v94, 1.0, v94
	v_add_f32_e32 v90, 1.0, v90
	v_add_f32_e32 v91, 1.0, v91
	v_add_f32_e32 v92, 1.0, v92
	v_add_f32_e32 v93, 1.0, v93
	v_mul_f32_e32 v82, 0xbfb8aa3b, v82
	v_mul_f32_e32 v83, 0xbfb8aa3b, v83
	v_mul_f32_e32 v84, 0xbfb8aa3b, v84
	v_rcp_f32_e32 v94, v94
	v_rcp_f32_e32 v90, v90
	v_rcp_f32_e32 v91, v91
	v_rcp_f32_e32 v92, v92
	v_rcp_f32_e32 v93, v93
	v_exp_f32_e32 v82, v82
	v_exp_f32_e32 v83, v83
	v_exp_f32_e32 v84, v84
	s_or_b32 s12, s44, 8
	s_ashr_i32 s13, s12, 31
	s_lshl_b64 s[12:13], s[12:13], 13
	v_cvt_pk_bf16_f32 v90, v94, v90
	v_cvt_pk_bf16_f32 v91, v91, v92
	v_cvt_pk_bf16_f32 v92, v98, v95
	v_cvt_pk_bf16_f32 v93, v96, v93
	v_lshl_add_u64 v[94:95], v[146:147], 0, s[12:13]
	v_pk_add_f32 v[88:89], v[88:89], v[204:205]
	v_pk_add_f32 v[86:87], v[86:87], v[202:203]
	v_add_f32_e32 v82, 1.0, v82
	v_add_f32_e32 v83, 1.0, v83
	v_add_f32_e32 v84, 1.0, v84
	global_store_dwordx4 v[94:95], v[90:93], off
	v_mul_f32_e32 v86, 0xbfb8aa3b, v86
	v_mul_f32_e32 v85, 0xbfb8aa3b, v85
	v_rcp_f32_e32 v90, v82
	v_mul_f32_e32 v82, 0xbfb8aa3b, v87
	v_rcp_f32_e32 v87, v83
	v_mul_f32_e32 v83, 0xbfb8aa3b, v88
	v_rcp_f32_e32 v88, v84
	v_mul_f32_e32 v84, 0xbfb8aa3b, v89
	v_exp_f32_e32 v86, v86
	v_exp_f32_e32 v82, v82
	v_exp_f32_e32 v83, v83
	v_exp_f32_e32 v84, v84
	v_exp_f32_e32 v85, v85
	v_pk_add_f32 v[76:77], v[76:77], v[208:209]
	v_pk_add_f32 v[74:75], v[74:75], v[206:207]
	v_add_f32_e32 v86, 1.0, v86
	v_add_f32_e32 v82, 1.0, v82
	v_add_f32_e32 v83, 1.0, v83
	v_add_f32_e32 v84, 1.0, v84
	v_add_f32_e32 v85, 1.0, v85
	v_mul_f32_e32 v74, 0xbfb8aa3b, v74
	v_mul_f32_e32 v75, 0xbfb8aa3b, v75
	v_mul_f32_e32 v76, 0xbfb8aa3b, v76
	v_rcp_f32_e32 v86, v86
	v_rcp_f32_e32 v82, v82
	v_rcp_f32_e32 v83, v83
	v_rcp_f32_e32 v84, v84
	v_rcp_f32_e32 v85, v85
	v_exp_f32_e32 v74, v74
	v_exp_f32_e32 v75, v75
	v_exp_f32_e32 v76, v76
	s_or_b32 s12, s44, 9
	s_ashr_i32 s13, s12, 31
	s_lshl_b64 s[12:13], s[12:13], 13
	v_cvt_pk_bf16_f32 v82, v86, v82
	v_cvt_pk_bf16_f32 v83, v83, v84
	v_cvt_pk_bf16_f32 v84, v90, v87
	v_cvt_pk_bf16_f32 v85, v88, v85
	v_lshl_add_u64 v[86:87], v[146:147], 0, s[12:13]
	v_pk_add_f32 v[80:81], v[80:81], v[204:205]
	v_pk_add_f32 v[78:79], v[78:79], v[202:203]
	v_add_f32_e32 v74, 1.0, v74
	v_add_f32_e32 v75, 1.0, v75
	v_add_f32_e32 v76, 1.0, v76
	global_store_dwordx4 v[86:87], v[82:85], off
	v_mul_f32_e32 v78, 0xbfb8aa3b, v78
	v_mul_f32_e32 v77, 0xbfb8aa3b, v77
	v_rcp_f32_e32 v82, v74
	v_mul_f32_e32 v74, 0xbfb8aa3b, v79
	v_rcp_f32_e32 v79, v75
	v_mul_f32_e32 v75, 0xbfb8aa3b, v80
	v_rcp_f32_e32 v80, v76
	v_mul_f32_e32 v76, 0xbfb8aa3b, v81
	v_exp_f32_e32 v78, v78
	v_exp_f32_e32 v74, v74
	v_exp_f32_e32 v75, v75
	v_exp_f32_e32 v76, v76
	v_exp_f32_e32 v77, v77
	v_pk_add_f32 v[68:69], v[68:69], v[208:209]
	v_pk_add_f32 v[66:67], v[66:67], v[206:207]
	v_add_f32_e32 v78, 1.0, v78
	v_add_f32_e32 v74, 1.0, v74
	v_add_f32_e32 v75, 1.0, v75
	v_add_f32_e32 v76, 1.0, v76
	v_add_f32_e32 v77, 1.0, v77
	v_mul_f32_e32 v66, 0xbfb8aa3b, v66
	v_mul_f32_e32 v67, 0xbfb8aa3b, v67
	v_mul_f32_e32 v68, 0xbfb8aa3b, v68
	v_rcp_f32_e32 v78, v78
	v_rcp_f32_e32 v74, v74
	v_rcp_f32_e32 v75, v75
	v_rcp_f32_e32 v76, v76
	v_rcp_f32_e32 v77, v77
	v_exp_f32_e32 v66, v66
	v_exp_f32_e32 v67, v67
	v_exp_f32_e32 v68, v68
	s_or_b32 s12, s44, 10
	s_ashr_i32 s13, s12, 31
	s_lshl_b64 s[12:13], s[12:13], 13
	v_cvt_pk_bf16_f32 v74, v78, v74
	v_cvt_pk_bf16_f32 v75, v75, v76
	v_cvt_pk_bf16_f32 v76, v82, v79
	v_cvt_pk_bf16_f32 v77, v80, v77
	v_lshl_add_u64 v[78:79], v[146:147], 0, s[12:13]
	v_pk_add_f32 v[72:73], v[72:73], v[204:205]
	v_pk_add_f32 v[70:71], v[70:71], v[202:203]
	v_add_f32_e32 v66, 1.0, v66
	v_add_f32_e32 v67, 1.0, v67
	v_add_f32_e32 v68, 1.0, v68
	global_store_dwordx4 v[78:79], v[74:77], off
; __device__ __forceinline__ unsigned cvt_pk_bf16(float lo, float hi) { const f32x2 v = {lo, hi}; const bf16x2_t b = __builtin_convertvector(v, bf16x2_t); return __builtin_bit_cast(unsigned, b); }
; __device__ __forceinline__ float fast_sigmoid(float x) { return __builtin_amdgcn_rcpf(1.0f + __builtin_amdgcn_exp2f(-x * LOG2E)); }
;     __device__ __forceinline__ void operator()(const f32x4 (&acc)[2][2][4][2], const Unit& u, int wr, int wc, int fr, int fq) const {
;     ...
;             for (int bj = 0; bj < 2; ++bj) { const f32x4 b0 = *(const f32x4*)(bgate + br * 1024 + col00 + bj * 128), b1 = *(const f32x4*)(bgate + br * 1024 + col00 + bj * 128 + 4);
; #pragma unroll
;                 for (int ai = 0; ai < 2; ++ai)
; #pragma unroll
;                     for (int m = 0; m < 4; ++m) { f32x4 v0 = acc[ai][bj][m][0] + b0, v1 = acc[ai][bj][m][1] + b1;
; #pragma unroll
;                         for (int i = 0; i < 4; ++i) { v0[i] = fast_sigmoid(v0[i]); v1[i] = fast_sigmoid(v1[i]); }
;                         u32x4 w; w.x = cvt_pk_bf16(v0[0], v0[1]); w.y = cvt_pk_bf16(v0[2], v0[3]); w.z = cvt_pk_bf16(v1[0], v1[1]); w.w = cvt_pk_bf16(v1[2], v1[3]);
;                         *((u32x4*)Gs + ((size_t)(tile * 16 + (ai * 2 + bj) * 4 + m) * NTHREADS + tid)) = w; } }
	v_mul_f32_e32 v70, 0xbfb8aa3b, v70
	v_mul_f32_e32 v69, 0xbfb8aa3b, v69
	v_rcp_f32_e32 v74, v66
	v_mul_f32_e32 v66, 0xbfb8aa3b, v71
	v_rcp_f32_e32 v71, v67
	v_mul_f32_e32 v67, 0xbfb8aa3b, v72
	v_rcp_f32_e32 v72, v68
	v_mul_f32_e32 v68, 0xbfb8aa3b, v73
	v_exp_f32_e32 v70, v70
	v_exp_f32_e32 v66, v66
	v_exp_f32_e32 v67, v67
	v_exp_f32_e32 v68, v68
	v_exp_f32_e32 v69, v69
	v_add_f32_e32 v70, 1.0, v70
	v_add_f32_e32 v66, 1.0, v66
	v_add_f32_e32 v67, 1.0, v67
	v_add_f32_e32 v68, 1.0, v68
	v_add_f32_e32 v69, 1.0, v69
	v_rcp_f32_e32 v70, v70
	v_rcp_f32_e32 v66, v66
	v_rcp_f32_e32 v67, v67
	v_rcp_f32_e32 v68, v68
	v_rcp_f32_e32 v69, v69
	s_or_b32 s12, s44, 11
	s_ashr_i32 s13, s12, 31
	s_lshl_b64 s[12:13], s[12:13], 13
	v_cvt_pk_bf16_f32 v66, v70, v66
	v_cvt_pk_bf16_f32 v67, v67, v68
	v_cvt_pk_bf16_f32 v68, v74, v71
	v_cvt_pk_bf16_f32 v69, v72, v69
	v_lshl_add_u64 v[70:71], v[146:147], 0, s[12:13]
	global_store_dwordx4 v[70:71], v[66:69], off
	s_nop 0
	s_or_b32 s12, s44, 4
	s_ashr_i32 s13, s12, 31
	s_lshl_b64 s[12:13], s[12:13], 13
	v_pk_add_f32 v[60:61], v[60:61], v[216:217]
	v_pk_add_f32 v[58:59], v[58:59], v[214:215]
	v_mul_f32_e32 v60, 0xbfb8aa3b, v60
	v_mul_f32_e32 v58, 0xbfb8aa3b, v58
	v_mul_f32_e32 v59, 0xbfb8aa3b, v59
	v_exp_f32_e32 v58, v58
	v_exp_f32_e32 v59, v59
	v_exp_f32_e32 v60, v60
	v_pk_add_f32 v[64:65], v[64:65], v[212:213]
	v_pk_add_f32 v[62:63], v[62:63], v[210:211]
	v_add_f32_e32 v58, 1.0, v58
	v_add_f32_e32 v59, 1.0, v59
	v_add_f32_e32 v60, 1.0, v60
	v_mul_f32_e32 v62, 0xbfb8aa3b, v62
	v_rcp_f32_e32 v74, v58
	v_mul_f32_e32 v58, 0xbfb8aa3b, v63
	v_rcp_f32_e32 v63, v59
	v_mul_f32_e32 v59, 0xbfb8aa3b, v64
	v_rcp_f32_e32 v64, v60
	v_mul_f32_e32 v60, 0xbfb8aa3b, v65
	v_mul_f32_e32 v61, 0xbfb8aa3b, v61
	v_exp_f32_e32 v62, v62
	v_exp_f32_e32 v58, v58
	v_exp_f32_e32 v59, v59
	v_exp_f32_e32 v60, v60
	v_exp_f32_e32 v61, v61
	v_pk_add_f32 v[52:53], v[52:53], v[216:217]
	v_pk_add_f32 v[50:51], v[50:51], v[214:215]
	v_add_f32_e32 v62, 1.0, v62
	v_add_f32_e32 v58, 1.0, v58
	v_add_f32_e32 v59, 1.0, v59
	v_add_f32_e32 v60, 1.0, v60
	v_add_f32_e32 v61, 1.0, v61
	v_mul_f32_e32 v50, 0xbfb8aa3b, v50
	v_mul_f32_e32 v51, 0xbfb8aa3b, v51
	v_mul_f32_e32 v52, 0xbfb8aa3b, v52
	v_rcp_f32_e32 v62, v62
	v_rcp_f32_e32 v58, v58
	v_rcp_f32_e32 v59, v59
	v_rcp_f32_e32 v60, v60
	v_rcp_f32_e32 v61, v61
	v_exp_f32_e32 v50, v50
	v_exp_f32_e32 v51, v51
	v_exp_f32_e32 v52, v52
	v_cvt_pk_bf16_f32 v58, v62, v58
	v_cvt_pk_bf16_f32 v59, v59, v60
	v_cvt_pk_bf16_f32 v60, v74, v63
	v_cvt_pk_bf16_f32 v61, v64, v61
	v_lshl_add_u64 v[62:63], v[146:147], 0, s[12:13]
	v_pk_add_f32 v[56:57], v[56:57], v[212:213]
	v_pk_add_f32 v[54:55], v[54:55], v[210:211]
	v_add_f32_e32 v50, 1.0, v50
	v_add_f32_e32 v51, 1.0, v51
	v_add_f32_e32 v52, 1.0, v52
	v_mov_b32_e32 v246, v58
	v_mov_b32_e32 v247, v59
	v_mov_b32_e32 v248, v60
	v_mov_b32_e32 v249, v61
	v_mul_f32_e32 v54, 0xbfb8aa3b, v54
	v_mul_f32_e32 v53, 0xbfb8aa3b, v53
	v_rcp_f32_e32 v58, v50
	v_mul_f32_e32 v50, 0xbfb8aa3b, v55
	v_rcp_f32_e32 v55, v51
	v_mul_f32_e32 v51, 0xbfb8aa3b, v56
	v_rcp_f32_e32 v56, v52
	v_mul_f32_e32 v52, 0xbfb8aa3b, v57
	v_exp_f32_e32 v54, v54
	v_exp_f32_e32 v50, v50
	v_exp_f32_e32 v51, v51
	v_exp_f32_e32 v52, v52
	v_exp_f32_e32 v53, v53
	v_pk_add_f32 v[44:45], v[44:45], v[216:217]
	v_pk_add_f32 v[42:43], v[42:43], v[214:215]
	v_add_f32_e32 v54, 1.0, v54
	v_add_f32_e32 v50, 1.0, v50
	v_add_f32_e32 v51, 1.0, v51
	v_add_f32_e32 v52, 1.0, v52
	v_add_f32_e32 v53, 1.0, v53
	v_mul_f32_e32 v42, 0xbfb8aa3b, v42
	v_mul_f32_e32 v43, 0xbfb8aa3b, v43
	v_mul_f32_e32 v44, 0xbfb8aa3b, v44
	v_rcp_f32_e32 v54, v54
	v_rcp_f32_e32 v50, v50
	v_rcp_f32_e32 v51, v51
	v_rcp_f32_e32 v52, v52
	v_rcp_f32_e32 v53, v53
	v_exp_f32_e32 v42, v42
	v_exp_f32_e32 v43, v43
	v_exp_f32_e32 v44, v44
	s_or_b32 s12, s44, 5
	s_ashr_i32 s13, s12, 31
	s_lshl_b64 s[12:13], s[12:13], 13
	v_cvt_pk_bf16_f32 v50, v54, v50
	v_cvt_pk_bf16_f32 v51, v51, v52
	v_cvt_pk_bf16_f32 v52, v58, v55
	v_cvt_pk_bf16_f32 v53, v56, v53
	v_lshl_add_u64 v[54:55], v[146:147], 0, s[12:13]
	v_pk_add_f32 v[48:49], v[48:49], v[212:213]
	v_pk_add_f32 v[46:47], v[46:47], v[210:211]
	v_add_f32_e32 v42, 1.0, v42
	v_add_f32_e32 v43, 1.0, v43
	v_add_f32_e32 v44, 1.0, v44
	v_mov_b32_e32 v198, v50
	v_mov_b32_e32 v199, v51
	v_mov_b32_e32 v200, v52
	v_mov_b32_e32 v201, v53
	v_mul_f32_e32 v46, 0xbfb8aa3b, v46
	v_mul_f32_e32 v45, 0xbfb8aa3b, v45
	v_rcp_f32_e32 v50, v42
	v_mul_f32_e32 v42, 0xbfb8aa3b, v47
	v_rcp_f32_e32 v47, v43
	v_mul_f32_e32 v43, 0xbfb8aa3b, v48
	v_rcp_f32_e32 v48, v44
	v_mul_f32_e32 v44, 0xbfb8aa3b, v49
	v_exp_f32_e32 v46, v46
	v_exp_f32_e32 v42, v42
	v_exp_f32_e32 v43, v43
	v_exp_f32_e32 v44, v44
	v_exp_f32_e32 v45, v45
	v_pk_add_f32 v[36:37], v[36:37], v[216:217]
	v_pk_add_f32 v[34:35], v[34:35], v[214:215]
	v_add_f32_e32 v46, 1.0, v46
	v_add_f32_e32 v42, 1.0, v42
	v_add_f32_e32 v43, 1.0, v43
	v_add_f32_e32 v44, 1.0, v44
	v_add_f32_e32 v45, 1.0, v45
	v_mul_f32_e32 v34, 0xbfb8aa3b, v34
	v_mul_f32_e32 v35, 0xbfb8aa3b, v35
	v_mul_f32_e32 v36, 0xbfb8aa3b, v36
	v_rcp_f32_e32 v46, v46
	v_rcp_f32_e32 v42, v42
	v_rcp_f32_e32 v43, v43
	v_rcp_f32_e32 v44, v44
	v_rcp_f32_e32 v45, v45
	v_exp_f32_e32 v34, v34
	v_exp_f32_e32 v35, v35
	v_exp_f32_e32 v36, v36
	s_or_b32 s12, s44, 6
	s_ashr_i32 s13, s12, 31
	s_lshl_b64 s[12:13], s[12:13], 13
	v_cvt_pk_bf16_f32 v42, v46, v42
	v_cvt_pk_bf16_f32 v43, v43, v44
	v_cvt_pk_bf16_f32 v44, v50, v47
	v_cvt_pk_bf16_f32 v45, v48, v45
	v_lshl_add_u64 v[46:47], v[146:147], 0, s[12:13]
	v_pk_add_f32 v[40:41], v[40:41], v[212:213]
	v_pk_add_f32 v[38:39], v[38:39], v[210:211]
	v_add_f32_e32 v34, 1.0, v34
	v_add_f32_e32 v35, 1.0, v35
	v_add_f32_e32 v36, 1.0, v36
; __device__ __forceinline__ unsigned cvt_pk_bf16(float lo, float hi) { const f32x2 v = {lo, hi}; const bf16x2_t b = __builtin_convertvector(v, bf16x2_t); return __builtin_bit_cast(unsigned, b); }
; __device__ __forceinline__ float fast_sigmoid(float x) { return __builtin_amdgcn_rcpf(1.0f + __builtin_amdgcn_exp2f(-x * LOG2E)); }
;     __device__ __forceinline__ void operator()(const f32x4 (&acc)[2][2][4][2], const Unit& u, int wr, int wc, int fr, int fq) const {
;     ...
;             for (int bj = 0; bj < 2; ++bj) { const f32x4 b0 = *(const f32x4*)(bgate + br * 1024 + col00 + bj * 128), b1 = *(const f32x4*)(bgate + br * 1024 + col00 + bj * 128 + 4);
; #pragma unroll
;                 for (int ai = 0; ai < 2; ++ai)
; #pragma unroll
;                     for (int m = 0; m < 4; ++m) { f32x4 v0 = acc[ai][bj][m][0] + b0, v1 = acc[ai][bj][m][1] + b1;
; #pragma unroll
;                         for (int i = 0; i < 4; ++i) { v0[i] = fast_sigmoid(v0[i]); v1[i] = fast_sigmoid(v1[i]); }
;                         u32x4 w; w.x = cvt_pk_bf16(v0[0], v0[1]); w.y = cvt_pk_bf16(v0[2], v0[3]); w.z = cvt_pk_bf16(v1[0], v1[1]); w.w = cvt_pk_bf16(v1[2], v1[3]);
;                         *((u32x4*)Gs + ((size_t)(tile * 16 + (ai * 2 + bj) * 4 + m) * NTHREADS + tid)) = w; } }
;             return;
	global_store_dwordx4 v[46:47], v[42:45], off
	v_mul_f32_e32 v38, 0xbfb8aa3b, v38
	v_mul_f32_e32 v37, 0xbfb8aa3b, v37
	v_rcp_f32_e32 v42, v34
	v_mul_f32_e32 v34, 0xbfb8aa3b, v39
	v_rcp_f32_e32 v39, v35
	v_mul_f32_e32 v35, 0xbfb8aa3b, v40
	v_rcp_f32_e32 v40, v36
	v_mul_f32_e32 v36, 0xbfb8aa3b, v41
	v_exp_f32_e32 v38, v38
	v_exp_f32_e32 v34, v34
	v_exp_f32_e32 v35, v35
	v_exp_f32_e32 v36, v36
	v_exp_f32_e32 v37, v37
	v_pk_add_f32 v[28:29], v[28:29], v[216:217]
	v_pk_add_f32 v[26:27], v[26:27], v[214:215]
	v_add_f32_e32 v38, 1.0, v38
	v_add_f32_e32 v34, 1.0, v34
	v_add_f32_e32 v35, 1.0, v35
	v_add_f32_e32 v36, 1.0, v36
	v_add_f32_e32 v37, 1.0, v37
	v_mul_f32_e32 v26, 0xbfb8aa3b, v26
	v_mul_f32_e32 v27, 0xbfb8aa3b, v27
	v_mul_f32_e32 v28, 0xbfb8aa3b, v28
	v_rcp_f32_e32 v38, v38
	v_rcp_f32_e32 v34, v34
	v_rcp_f32_e32 v35, v35
	v_rcp_f32_e32 v36, v36
	v_rcp_f32_e32 v37, v37
	v_exp_f32_e32 v26, v26
	v_exp_f32_e32 v27, v27
	v_exp_f32_e32 v28, v28
	s_or_b32 s12, s44, 7
	s_ashr_i32 s13, s12, 31
	s_lshl_b64 s[12:13], s[12:13], 13
	v_cvt_pk_bf16_f32 v34, v38, v34
	v_cvt_pk_bf16_f32 v35, v35, v36
	v_cvt_pk_bf16_f32 v36, v42, v39
	v_cvt_pk_bf16_f32 v37, v40, v37
	v_lshl_add_u64 v[38:39], v[146:147], 0, s[12:13]
	v_pk_add_f32 v[32:33], v[32:33], v[212:213]
	v_pk_add_f32 v[30:31], v[30:31], v[210:211]
	v_add_f32_e32 v26, 1.0, v26
	v_add_f32_e32 v27, 1.0, v27
	v_add_f32_e32 v28, 1.0, v28
	global_store_dwordx4 v[38:39], v[34:37], off
	v_mul_f32_e32 v30, 0xbfb8aa3b, v30
	v_mul_f32_e32 v29, 0xbfb8aa3b, v29
	v_rcp_f32_e32 v34, v26
	v_mul_f32_e32 v26, 0xbfb8aa3b, v31
	v_rcp_f32_e32 v31, v27
	v_mul_f32_e32 v27, 0xbfb8aa3b, v32
	v_rcp_f32_e32 v32, v28
	v_mul_f32_e32 v28, 0xbfb8aa3b, v33
	v_exp_f32_e32 v30, v30
	v_exp_f32_e32 v26, v26
	v_exp_f32_e32 v27, v27
	v_exp_f32_e32 v28, v28
	v_exp_f32_e32 v29, v29
	v_pk_add_f32 v[20:21], v[20:21], v[216:217]
	v_pk_add_f32 v[18:19], v[18:19], v[214:215]
	v_add_f32_e32 v30, 1.0, v30
	v_add_f32_e32 v26, 1.0, v26
	v_add_f32_e32 v27, 1.0, v27
	v_add_f32_e32 v28, 1.0, v28
	v_add_f32_e32 v29, 1.0, v29
	v_mul_f32_e32 v18, 0xbfb8aa3b, v18
	v_mul_f32_e32 v19, 0xbfb8aa3b, v19
	v_mul_f32_e32 v20, 0xbfb8aa3b, v20
	v_rcp_f32_e32 v30, v30
	v_rcp_f32_e32 v26, v26
	v_rcp_f32_e32 v27, v27
	v_rcp_f32_e32 v28, v28
	v_rcp_f32_e32 v29, v29
	v_exp_f32_e32 v18, v18
	v_exp_f32_e32 v19, v19
	v_exp_f32_e32 v20, v20
	s_or_b32 s12, s44, 12
	s_ashr_i32 s13, s12, 31
	s_lshl_b64 s[12:13], s[12:13], 13
	v_cvt_pk_bf16_f32 v26, v30, v26
	v_cvt_pk_bf16_f32 v27, v27, v28
	v_cvt_pk_bf16_f32 v28, v34, v31
	v_cvt_pk_bf16_f32 v29, v32, v29
	v_lshl_add_u64 v[30:31], v[146:147], 0, s[12:13]
	v_pk_add_f32 v[24:25], v[24:25], v[212:213]
	v_pk_add_f32 v[22:23], v[22:23], v[210:211]
	v_add_f32_e32 v18, 1.0, v18
	v_add_f32_e32 v19, 1.0, v19
	v_add_f32_e32 v20, 1.0, v20
	global_store_dwordx4 v[30:31], v[26:29], off
	v_mul_f32_e32 v22, 0xbfb8aa3b, v22
	v_mul_f32_e32 v21, 0xbfb8aa3b, v21
	v_rcp_f32_e32 v26, v18
	v_mul_f32_e32 v18, 0xbfb8aa3b, v23
	v_rcp_f32_e32 v23, v19
	v_mul_f32_e32 v19, 0xbfb8aa3b, v24
	v_rcp_f32_e32 v24, v20
	v_mul_f32_e32 v20, 0xbfb8aa3b, v25
	v_exp_f32_e32 v22, v22
	v_exp_f32_e32 v18, v18
	v_exp_f32_e32 v19, v19
	v_exp_f32_e32 v20, v20
	v_exp_f32_e32 v21, v21
	v_pk_add_f32 v[12:13], v[12:13], v[216:217]
	v_pk_add_f32 v[10:11], v[10:11], v[214:215]
	v_add_f32_e32 v22, 1.0, v22
	v_add_f32_e32 v18, 1.0, v18
	v_add_f32_e32 v19, 1.0, v19
	v_add_f32_e32 v20, 1.0, v20
	v_add_f32_e32 v21, 1.0, v21
	v_mul_f32_e32 v10, 0xbfb8aa3b, v10
	v_mul_f32_e32 v11, 0xbfb8aa3b, v11
	v_mul_f32_e32 v12, 0xbfb8aa3b, v12
	v_rcp_f32_e32 v22, v22
	v_rcp_f32_e32 v18, v18
	v_rcp_f32_e32 v19, v19
	v_rcp_f32_e32 v20, v20
	v_rcp_f32_e32 v21, v21
	v_exp_f32_e32 v10, v10
	v_exp_f32_e32 v11, v11
	v_exp_f32_e32 v12, v12
	s_or_b32 s12, s44, 13
	s_ashr_i32 s13, s12, 31
	s_lshl_b64 s[12:13], s[12:13], 13
	v_cvt_pk_bf16_f32 v18, v22, v18
	v_cvt_pk_bf16_f32 v19, v19, v20
	v_cvt_pk_bf16_f32 v20, v26, v23
	v_cvt_pk_bf16_f32 v21, v24, v21
	v_lshl_add_u64 v[22:23], v[146:147], 0, s[12:13]
	v_pk_add_f32 v[16:17], v[16:17], v[212:213]
	v_pk_add_f32 v[14:15], v[14:15], v[210:211]
	v_add_f32_e32 v10, 1.0, v10
	v_add_f32_e32 v11, 1.0, v11
	v_add_f32_e32 v12, 1.0, v12
	global_store_dwordx4 v[22:23], v[18:21], off
	v_mul_f32_e32 v14, 0xbfb8aa3b, v14
	v_mul_f32_e32 v13, 0xbfb8aa3b, v13
	v_rcp_f32_e32 v18, v10
	v_mul_f32_e32 v10, 0xbfb8aa3b, v15
	v_rcp_f32_e32 v15, v11
	v_mul_f32_e32 v11, 0xbfb8aa3b, v16
	v_rcp_f32_e32 v16, v12
	v_mul_f32_e32 v12, 0xbfb8aa3b, v17
	v_exp_f32_e32 v14, v14
	v_exp_f32_e32 v10, v10
	v_exp_f32_e32 v11, v11
	v_exp_f32_e32 v12, v12
	v_exp_f32_e32 v13, v13
	v_pk_add_f32 v[4:5], v[4:5], v[216:217]
	v_pk_add_f32 v[2:3], v[2:3], v[214:215]
	v_add_f32_e32 v14, 1.0, v14
	v_add_f32_e32 v10, 1.0, v10
	v_add_f32_e32 v11, 1.0, v11
	v_add_f32_e32 v12, 1.0, v12
	v_add_f32_e32 v13, 1.0, v13
	v_mul_f32_e32 v2, 0xbfb8aa3b, v2
	v_mul_f32_e32 v3, 0xbfb8aa3b, v3
	v_mul_f32_e32 v4, 0xbfb8aa3b, v4
	v_rcp_f32_e32 v14, v14
	v_rcp_f32_e32 v10, v10
	v_rcp_f32_e32 v11, v11
	v_rcp_f32_e32 v12, v12
	v_rcp_f32_e32 v13, v13
	v_exp_f32_e32 v2, v2
	v_exp_f32_e32 v3, v3
	v_exp_f32_e32 v4, v4
	s_or_b32 s12, s44, 14
	s_ashr_i32 s13, s12, 31
	s_lshl_b64 s[12:13], s[12:13], 13
	v_cvt_pk_bf16_f32 v10, v14, v10
	v_cvt_pk_bf16_f32 v11, v11, v12
	v_cvt_pk_bf16_f32 v12, v18, v15
	v_cvt_pk_bf16_f32 v13, v16, v13
	v_lshl_add_u64 v[14:15], v[146:147], 0, s[12:13]
	v_pk_add_f32 v[8:9], v[8:9], v[212:213]
	v_pk_add_f32 v[6:7], v[6:7], v[210:211]
	v_add_f32_e32 v2, 1.0, v2
	v_add_f32_e32 v3, 1.0, v3
	v_add_f32_e32 v4, 1.0, v4
	global_store_dwordx4 v[14:15], v[10:13], off
	v_mul_f32_e32 v6, 0xbfb8aa3b, v6
	v_mul_f32_e32 v5, 0xbfb8aa3b, v5
	v_rcp_f32_e32 v10, v2
	v_mul_f32_e32 v2, 0xbfb8aa3b, v7
	v_rcp_f32_e32 v7, v3
	v_mul_f32_e32 v3, 0xbfb8aa3b, v8
	v_rcp_f32_e32 v8, v4
	v_mul_f32_e32 v4, 0xbfb8aa3b, v9
	v_exp_f32_e32 v6, v6
	v_exp_f32_e32 v2, v2
	v_exp_f32_e32 v3, v3
	v_exp_f32_e32 v4, v4
	v_exp_f32_e32 v5, v5
	v_add_f32_e32 v6, 1.0, v6
	v_add_f32_e32 v2, 1.0, v2
	v_add_f32_e32 v3, 1.0, v3
	v_add_f32_e32 v4, 1.0, v4
	v_add_f32_e32 v5, 1.0, v5
	v_rcp_f32_e32 v6, v6
	v_rcp_f32_e32 v2, v2
	v_rcp_f32_e32 v3, v3
	v_rcp_f32_e32 v4, v4
	v_rcp_f32_e32 v5, v5
	s_or_b32 s12, s44, 15
	s_ashr_i32 s13, s12, 31
	s_lshl_b64 s[12:13], s[12:13], 13
	v_cvt_pk_bf16_f32 v2, v6, v2
	v_cvt_pk_bf16_f32 v3, v3, v4
	v_cvt_pk_bf16_f32 v4, v10, v7
	v_cvt_pk_bf16_f32 v5, v8, v5
	v_lshl_add_u64 v[6:7], v[146:147], 0, s[12:13]
	global_store_dwordx4 v[6:7], v[2:5], off
	s_and_b64 vcc, exec, s[42:43]
	s_mov_b64 s[12:13], -1
	s_cbranch_vccnz .LBB0_283
